# attention epilogue: 16 dwordx2 row-per-lane O stores widened to 8 dwordx4 via v_permlane32_swap pairs (doc 7.3), counted vmcnt re-derived; on top of ballot trim
# speedup vs baseline: 1.0022x; 1.0022x over previous
; __device__ __forceinline__ int crow(int i, int hh) { return (i & 3) + 8 * (i >> 2) + 4 * hh; }
;     ...
;         if (mi == 0) { float ssq = 0.f;
; #pragma unroll
;             for (int dt = 0; dt < 4; ++dt)
; #pragma unroll
;                 for (int i = 0; i < 16; ++i) { const float v = o[dt][i] * linv - ex[g * 4096 + (32 * dt + crow(i, hh)) * 32 + r]; o[dt][i] = v; ssq += v * v; }
;             ssq += __shfl_xor(ssq, 32);
;             const float rstd = outscale / sqrtf(ssq * (1.0f / 128.0f) + RMS_EPS);
;             bf16* op = Od + ((size_t)(b * SEQ + qabs)) * 1024 + h * 128 + 4 * hh;
; #pragma unroll
;             for (int dt = 0; dt < 4; ++dt)
; #pragma unroll
;                 for (int i4 = 0; i4 < 4; ++i4) { const int dv = 32 * dt + 8 * i4; const f32x4 sg = *(const f32x4*)(subln + dv + 4 * hh);
.LBB0_312:
	s_andn2_b64 vcc, exec, s[28:29]
	s_waitcnt lgkmcnt(0)
	s_setprio 0
	s_barrier
	s_cbranch_vccnz .LBB0_296
	global_load_dwordx4 v[96:99], v[192:193], off
	global_load_dwordx4 v[100:103], v[192:193], off offset:32
	global_load_dwordx4 v[104:107], v[192:193], off offset:64
	global_load_dwordx4 v[108:111], v[192:193], off offset:96
	global_load_dwordx4 v[112:115], v[192:193], off offset:128
	global_load_dwordx4 v[116:119], v[192:193], off offset:160
	global_load_dwordx4 v[120:123], v[192:193], off offset:192
	global_load_dwordx4 v[124:127], v[192:193], off offset:224
	global_load_dwordx4 v[128:131], v[192:193], off offset:256
	global_load_dwordx4 v[132:135], v[192:193], off offset:288
	global_load_dwordx4 v[136:139], v[192:193], off offset:320
	global_load_dwordx4 v[140:143], v[192:193], off offset:352
	global_load_dwordx4 v[144:147], v[192:193], off offset:384
	global_load_dwordx4 v[148:151], v[192:193], off offset:416
	global_load_dwordx4 v[152:155], v[192:193], off offset:448
	global_load_dwordx4 v[156:159], v[192:193], off offset:480
	ds_read2_b32 v[38:39], v224 offset1:32
	ds_read2_b32 v[40:41], v42 offset1:32
	ds_read2_b32 v[42:43], v42 offset0:64 offset1:96
	s_waitcnt lgkmcnt(2)
	v_fma_f32 v37, v64, v36, -v38
	v_fma_f32 v33, v65, v36, -v39
	ds_read2_b32 v[38:39], v224 offset0:64 offset1:96
	ds_read2_b32 v[64:65], v46 offset1:32
	ds_read2_b32 v[46:47], v46 offset0:64 offset1:96
	s_waitcnt lgkmcnt(3)
	v_fma_f32 v42, v70, v36, -v42
	v_fma_f32 v43, v71, v36, -v43
	s_waitcnt lgkmcnt(2)
	v_fma_f32 v38, v66, v36, -v38
	v_fma_f32 v39, v67, v36, -v39
	ds_read2_b32 v[66:67], v93 offset1:32
	s_waitcnt lgkmcnt(2)
	v_fma_f32 v45, v72, v36, -v64
	v_fma_f32 v44, v73, v36, -v65
	s_waitcnt lgkmcnt(1)
	v_fma_f32 v65, v74, v36, -v46
	v_fma_f32 v64, v75, v36, -v47
	s_waitcnt lgkmcnt(0)
	v_fma_f32 v47, v76, v36, -v66
	v_fma_f32 v46, v77, v36, -v67
	ds_read2_b32 v[66:67], v93 offset0:64 offset1:96
	ds_read2_b32 v[70:71], v92 offset1:32
	v_fma_f32 v40, v68, v36, -v40
	v_fma_f32 v41, v69, v36, -v41
	ds_read2_b32 v[72:73], v90 offset1:32
	s_waitcnt lgkmcnt(2)
	v_fma_f32 v68, v78, v36, -v66
	s_waitcnt lgkmcnt(1)
	v_fma_f32 v66, v48, v36, -v70
	v_fma_f32 v48, v49, v36, -v71
	ds_read2_b32 v[70:71], v92 offset0:64 offset1:96
	v_mul_f32_e32 v84, v33, v33
	v_fmac_f32_e32 v84, v37, v37
	v_fmac_f32_e32 v84, v38, v38
	v_fmac_f32_e32 v84, v39, v39
	s_waitcnt lgkmcnt(0)
	v_fma_f32 v69, v50, v36, -v70
	v_fma_f32 v51, v51, v36, -v71
	ds_read2_b32 v[70:71], v91 offset1:32
	v_fmac_f32_e32 v84, v40, v40
	v_fmac_f32_e32 v84, v41, v41
	v_fmac_f32_e32 v84, v42, v42
	v_fmac_f32_e32 v84, v43, v43
	s_waitcnt lgkmcnt(0)
	v_fma_f32 v50, v52, v36, -v70
	v_fma_f32 v49, v53, v36, -v71
	ds_read2_b32 v[52:53], v91 offset0:64 offset1:96
	v_fmac_f32_e32 v84, v45, v45
	v_fmac_f32_e32 v84, v44, v44
	v_fmac_f32_e32 v84, v65, v65
	v_fmac_f32_e32 v84, v64, v64
	s_waitcnt lgkmcnt(0)
	v_fma_f32 v70, v54, v36, -v52
	v_fma_f32 v54, v55, v36, -v53
	v_fma_f32 v53, v56, v36, -v72
	v_fma_f32 v52, v57, v36, -v73
	ds_read2_b32 v[56:57], v90 offset0:64 offset1:96
	ds_read2_b32 v[72:73], v89 offset1:32
	v_fmac_f32_e32 v84, v47, v47
	v_fmac_f32_e32 v84, v46, v46
	v_fmac_f32_e32 v84, v68, v68
	s_waitcnt lgkmcnt(1)
	v_fma_f32 v58, v58, v36, -v56
	s_waitcnt lgkmcnt(0)
	v_fma_f32 v56, v60, v36, -v72
	v_fma_f32 v55, v61, v36, -v73
	ds_read2_b32 v[72:73], v89 offset0:64 offset1:96
	v_fma_f32 v57, v59, v36, -v57
	v_fma_f32 v67, v79, v36, -v67
	v_fmac_f32_e32 v84, v67, v67
	v_fmac_f32_e32 v84, v66, v66
	s_waitcnt lgkmcnt(0)
	v_fma_f32 v61, v62, v36, -v72
	v_fma_f32 v60, v63, v36, -v73
	ds_read2_b32 v[62:63], v88 offset1:32
	ds_read2_b32 v[72:73], v87 offset1:32
	v_fmac_f32_e32 v84, v48, v48
	v_fmac_f32_e32 v84, v69, v69
	v_fmac_f32_e32 v84, v51, v51
	s_waitcnt lgkmcnt(1)
	v_fma_f32 v59, v16, v36, -v62
	v_fma_f32 v16, v17, v36, -v63
	ds_read2_b32 v[62:63], v88 offset0:64 offset1:96
	s_waitcnt lgkmcnt(1)
	v_fma_f32 v17, v21, v36, -v73
	v_fmac_f32_e32 v84, v50, v50
	v_fmac_f32_e32 v84, v49, v49
	v_fmac_f32_e32 v84, v70, v70
	s_waitcnt lgkmcnt(0)
	v_fma_f32 v62, v18, v36, -v62
	v_fma_f32 v18, v20, v36, -v72
	ds_read2_b32 v[20:21], v87 offset0:64 offset1:96
	ds_read2_b32 v[72:73], v86 offset1:32
	v_fma_f32 v19, v19, v36, -v63
	v_fmac_f32_e32 v84, v54, v54
	v_fmac_f32_e32 v84, v53, v53
	s_waitcnt lgkmcnt(1)
	v_fma_f32 v63, v22, v36, -v20
	v_fma_f32 v22, v23, v36, -v21
	s_waitcnt lgkmcnt(0)
	v_fma_f32 v21, v24, v36, -v72
	v_fma_f32 v20, v25, v36, -v73
	ds_read2_b32 v[24:25], v86 offset0:64 offset1:96
	ds_read2_b32 v[72:73], v85 offset1:32
	v_fmac_f32_e32 v84, v52, v52
	v_fmac_f32_e32 v84, v58, v58
	v_fmac_f32_e32 v84, v57, v57
	s_waitcnt lgkmcnt(1)
	v_fma_f32 v26, v26, v36, -v24
	s_waitcnt lgkmcnt(0)
	v_fma_f32 v24, v28, v36, -v72
	v_fma_f32 v23, v29, v36, -v73
	ds_read2_b32 v[28:29], v85 offset0:64 offset1:96
	ds_read2_b32 v[72:73], v83 offset1:32
	v_fmac_f32_e32 v84, v56, v56
	v_fma_f32 v25, v27, v36, -v25
	v_fmac_f32_e32 v84, v55, v55
	s_waitcnt lgkmcnt(1)
	v_fma_f32 v71, v30, v36, -v28
	v_fma_f32 v30, v31, v36, -v29
	s_waitcnt lgkmcnt(0)
	v_fma_f32 v29, v0, v36, -v72
	v_fma_f32 v27, v1, v36, -v73
	ds_read2_b32 v[0:1], v83 offset0:64 offset1:96
	v_fmac_f32_e32 v84, v61, v61
	v_fmac_f32_e32 v84, v60, v60
	v_fmac_f32_e32 v84, v59, v59
	v_fmac_f32_e32 v84, v16, v16
	s_waitcnt lgkmcnt(0)
	v_fma_f32 v77, v2, v36, -v0
	v_fma_f32 v76, v3, v36, -v1
	ds_read2_b32 v[0:1], v82 offset1:32
	v_fmac_f32_e32 v84, v62, v62
	v_fmac_f32_e32 v84, v19, v19
	v_fmac_f32_e32 v84, v18, v18
	v_fmac_f32_e32 v84, v17, v17
	v_fmac_f32_e32 v84, v63, v63
	s_waitcnt lgkmcnt(0)
; __device__ __forceinline__ unsigned cvtpk(float lo, float hi) { return pg8::cvt_pk_bf16(lo, hi); }
;     ...
;             ssq += __shfl_xor(ssq, 32);
;             const float rstd = outscale / sqrtf(ssq * (1.0f / 128.0f) + RMS_EPS);
;             bf16* op = Od + ((size_t)(b * SEQ + qabs)) * 1024 + h * 128 + 4 * hh;
; #pragma unroll
;             for (int dt = 0; dt < 4; ++dt)
; #pragma unroll
;                 for (int i4 = 0; i4 < 4; ++i4) { const int dv = 32 * dt + 8 * i4; const f32x4 sg = *(const f32x4*)(subln + dv + 4 * hh);
;                     v2u wv; wv.x = cvtpk(o[dt][4 * i4] * rstd * sg[0], o[dt][4 * i4 + 1] * rstd * sg[1]); wv.y = cvtpk(o[dt][4 * i4 + 2] * rstd * sg[2], o[dt][4 * i4 + 3] * rstd * sg[3]);
;                     *(v2u*)(op + dv) = wv; }
	v_fma_f32 v74, v4, v36, -v0
	v_fma_f32 v73, v5, v36, -v1
	ds_read2_b32 v[0:1], v82 offset0:64 offset1:96
	v_fmac_f32_e32 v84, v22, v22
	v_fmac_f32_e32 v84, v21, v21
	v_fmac_f32_e32 v84, v20, v20
	v_fmac_f32_e32 v84, v26, v26
	v_fmac_f32_e32 v84, v25, v25
	s_waitcnt lgkmcnt(0)
	v_fma_f32 v78, v6, v36, -v0
	v_fma_f32 v75, v7, v36, -v1
	ds_read2_b32 v[0:1], v81 offset1:32
	v_fmac_f32_e32 v84, v24, v24
	v_fmac_f32_e32 v84, v23, v23
	v_fmac_f32_e32 v84, v71, v71
	v_fmac_f32_e32 v84, v30, v30
	v_fmac_f32_e32 v84, v29, v29
	s_waitcnt lgkmcnt(0)
	v_fma_f32 v72, v8, v36, -v0
	v_fma_f32 v31, v9, v36, -v1
	ds_read2_b32 v[0:1], v81 offset0:64 offset1:96
	v_fmac_f32_e32 v84, v27, v27
	v_fmac_f32_e32 v84, v77, v77
	v_fmac_f32_e32 v84, v76, v76
	v_fmac_f32_e32 v84, v74, v74
	v_fmac_f32_e32 v84, v73, v73
	s_waitcnt lgkmcnt(0)
	v_fma_f32 v28, v10, v36, -v0
	v_fma_f32 v10, v11, v36, -v1
	ds_read2_b32 v[0:1], v80 offset1:32
	v_fmac_f32_e32 v84, v78, v78
	v_fmac_f32_e32 v84, v75, v75
	v_fmac_f32_e32 v84, v72, v72
	v_fmac_f32_e32 v84, v31, v31
	v_fmac_f32_e32 v84, v28, v28
	s_waitcnt lgkmcnt(0)
	v_pk_fma_f32 v[6:7], v[12:13], v[36:37], v[0:1] op_sel_hi:[1,0,1] neg_lo:[0,0,1] neg_hi:[0,0,1]
	v_fmac_f32_e32 v84, v10, v10
	v_pk_mul_f32 v[0:1], v[6:7], v[6:7]
	s_nop 0
	v_add_f32_e32 v0, v84, v0
	v_add_f32_e32 v2, v0, v1
	ds_read2_b32 v[0:1], v80 offset0:64 offset1:96
	s_waitcnt lgkmcnt(0)
	v_pk_fma_f32 v[4:5], v[14:15], v[36:37], v[0:1] op_sel_hi:[1,0,1] neg_lo:[0,0,1] neg_hi:[0,0,1]
	s_nop 0
	v_pk_mul_f32 v[0:1], v[4:5], v[4:5]
	s_nop 0
	v_add_f32_e32 v0, v2, v0
	v_and_b32_e32 v2, 64, v233
	v_add_f32_e32 v0, v0, v1
	v_xor_b32_e32 v1, 32, v233
	v_add_u32_e32 v2, 64, v2
	v_cmp_lt_i32_e32 vcc, v1, v2
	s_nop 1
	v_cndmask_b32_e32 v1, v233, v1, vcc
	v_lshlrev_b32_e32 v1, 2, v1
	ds_bpermute_b32 v1, v1, v0
	s_waitcnt lgkmcnt(0)
	v_add_f32_e32 v0, v0, v1
	v_fmamk_f32 v0, v0, 0x3c000000, v231
	v_cmp_gt_f32_e32 vcc, s73, v0
	v_mul_f32_e32 v1, 0x4f800000, v0
	s_nop 0
	v_cndmask_b32_e32 v0, v0, v1, vcc
	v_sqrt_f32_e32 v1, v0
	s_nop 0
	v_add_u32_e32 v2, -1, v1
	v_fma_f32 v3, -v2, v1, v0
	v_cmp_ge_f32_e64 s[40:41], 0, v3
	v_add_u32_e32 v3, 1, v1
	s_nop 0
	v_cndmask_b32_e64 v2, v1, v2, s[40:41]
	v_fma_f32 v1, -v3, v1, v0
	v_cmp_lt_f32_e64 s[40:41], 0, v1
	s_nop 1
	v_cndmask_b32_e64 v1, v2, v3, s[40:41]
	v_mul_f32_e32 v2, 0x37800000, v1
	v_cndmask_b32_e32 v1, v1, v2, vcc
	v_cmp_class_f32_e32 vcc, v0, v232
	s_nop 1
	v_cndmask_b32_e32 v0, v1, v0, vcc
	v_div_scale_f32 v1, s[4:5], v0, v0, v215
	v_rcp_f32_e32 v2, v1
	s_nop 0
	v_fma_f32 v3, -v1, v2, 1.0
	v_fmac_f32_e32 v2, v3, v2
	v_div_scale_f32 v3, vcc, v215, v0, v215
	v_mul_f32_e32 v8, v3, v2
	v_fma_f32 v9, -v1, v8, v3
	v_fmac_f32_e32 v8, v9, v2
	v_fma_f32 v1, -v1, v8, v3
	v_div_fmas_f32 v1, v1, v2, v8
	v_div_fixup_f32 v11, v1, v0, v215
	v_mul_f32_e32 v12, v37, v11
	v_lshl_add_u64 v[8:9], v[34:35], 1, v[190:191]
	v_mbcnt_lo_u32_b32 v170, -1, 0
	v_mbcnt_hi_u32_b32 v170, -1, v170
	v_and_b32_e32 v170, 32, v170
	v_lshrrev_b32_e32 v170, 2, v170
	v_mov_b32_e32 v171, 0
	v_lshl_add_u64 v[8:9], v[8:9], 0, v[170:171]
	v_mul_f32_e32 v6, v6, v11
	s_waitcnt vmcnt(15)
	v_mul_f32_e32 v160, v96, v12
	v_mul_f32_e32 v12, v33, v11
	v_mul_f32_e32 v161, v97, v12
	v_cvt_pk_bf16_f32 v160, v160, v161
	v_mul_f32_e32 v161, v38, v11
	v_mul_f32_e32 v161, v98, v161
	v_mul_f32_e32 v168, v39, v11
	v_mul_f32_e32 v168, v99, v168
	v_cvt_pk_bf16_f32 v161, v161, v168
	v_mul_f32_e32 v12, v40, v11
	s_waitcnt vmcnt(14)
	v_mul_f32_e32 v162, v100, v12
	v_mul_f32_e32 v12, v41, v11
	v_mul_f32_e32 v163, v101, v12
	v_cvt_pk_bf16_f32 v162, v162, v163
	v_mul_f32_e32 v163, v42, v11
	v_mul_f32_e32 v163, v102, v163
	v_mul_f32_e32 v168, v43, v11
	v_mul_f32_e32 v168, v103, v168
	v_cvt_pk_bf16_f32 v163, v163, v168
	s_nop 1
	v_permlane32_swap_b32_e32 v160, v162
	v_permlane32_swap_b32_e32 v161, v163
	global_store_dwordx4 v[8:9], v[160:163], off
	v_mul_f32_e32 v12, v45, v11
	s_waitcnt vmcnt(14)
	v_mul_f32_e32 v164, v12, v104
	v_mul_f32_e32 v12, v44, v11
	v_mul_f32_e32 v165, v12, v105
	v_cvt_pk_bf16_f32 v164, v164, v165
	v_mul_f32_e32 v165, v65, v11
	v_mul_f32_e32 v165, v165, v106
	v_mul_f32_e32 v168, v64, v11
	v_mul_f32_e32 v168, v168, v107
	v_cvt_pk_bf16_f32 v165, v165, v168
	v_mul_f32_e32 v12, v47, v11
	s_waitcnt vmcnt(13)
	v_mul_f32_e32 v166, v12, v108
	v_mul_f32_e32 v12, v46, v11
	v_mul_f32_e32 v167, v12, v109
	v_cvt_pk_bf16_f32 v166, v166, v167
	v_mul_f32_e32 v167, v68, v11
	v_mul_f32_e32 v167, v167, v110
	v_mul_f32_e32 v168, v67, v11
	v_mul_f32_e32 v168, v168, v111
	v_cvt_pk_bf16_f32 v167, v167, v168
	s_nop 1
	v_permlane32_swap_b32_e32 v164, v166
	v_permlane32_swap_b32_e32 v165, v167
	global_store_dwordx4 v[8:9], v[164:167], off offset:32
	v_mul_f32_e32 v12, v66, v11
	s_waitcnt vmcnt(13)
; __device__ __forceinline__ unsigned cvtpk(float lo, float hi) { return pg8::cvt_pk_bf16(lo, hi); }
;     ...
;             for (int dt = 0; dt < 4; ++dt)
; #pragma unroll
;                 for (int i4 = 0; i4 < 4; ++i4) { const int dv = 32 * dt + 8 * i4; const f32x4 sg = *(const f32x4*)(subln + dv + 4 * hh);
;                     v2u wv; wv.x = cvtpk(o[dt][4 * i4] * rstd * sg[0], o[dt][4 * i4 + 1] * rstd * sg[1]); wv.y = cvtpk(o[dt][4 * i4 + 2] * rstd * sg[2], o[dt][4 * i4 + 3] * rstd * sg[3]);
;                     *(v2u*)(op + dv) = wv; }
	v_mul_f32_e32 v160, v12, v112
	v_mul_f32_e32 v12, v48, v11
	v_mul_f32_e32 v161, v12, v113
	v_cvt_pk_bf16_f32 v160, v160, v161
	v_mul_f32_e32 v161, v69, v11
	v_mul_f32_e32 v161, v161, v114
	v_mul_f32_e32 v168, v51, v11
	v_mul_f32_e32 v168, v168, v115
	v_cvt_pk_bf16_f32 v161, v161, v168
	v_mul_f32_e32 v12, v50, v11
	s_waitcnt vmcnt(12)
	v_mul_f32_e32 v162, v12, v116
	v_mul_f32_e32 v12, v49, v11
	v_mul_f32_e32 v163, v12, v117
	v_cvt_pk_bf16_f32 v162, v162, v163
	v_mul_f32_e32 v163, v70, v11
	v_mul_f32_e32 v163, v163, v118
	v_mul_f32_e32 v168, v54, v11
	v_mul_f32_e32 v168, v168, v119
	v_cvt_pk_bf16_f32 v163, v163, v168
	s_nop 1
	v_permlane32_swap_b32_e32 v160, v162
	v_permlane32_swap_b32_e32 v161, v163
	global_store_dwordx4 v[8:9], v[160:163], off offset:64
	v_mul_f32_e32 v12, v53, v11
	s_waitcnt vmcnt(12)
	v_mul_f32_e32 v164, v12, v120
	v_mul_f32_e32 v12, v52, v11
	v_mul_f32_e32 v165, v12, v121
	v_cvt_pk_bf16_f32 v164, v164, v165
	v_mul_f32_e32 v165, v58, v11
	v_mul_f32_e32 v165, v165, v122
	v_mul_f32_e32 v168, v57, v11
	v_mul_f32_e32 v168, v168, v123
	v_cvt_pk_bf16_f32 v165, v165, v168
	v_mul_f32_e32 v12, v56, v11
	s_waitcnt vmcnt(11)
	v_mul_f32_e32 v166, v12, v124
	v_mul_f32_e32 v12, v55, v11
	v_mul_f32_e32 v167, v12, v125
	v_cvt_pk_bf16_f32 v166, v166, v167
	v_mul_f32_e32 v167, v61, v11
	v_mul_f32_e32 v167, v167, v126
	v_mul_f32_e32 v168, v60, v11
	v_mul_f32_e32 v168, v168, v127
	v_cvt_pk_bf16_f32 v167, v167, v168
	s_nop 1
	v_permlane32_swap_b32_e32 v164, v166
	v_permlane32_swap_b32_e32 v165, v167
	global_store_dwordx4 v[8:9], v[164:167], off offset:96
	v_mul_f32_e32 v12, v59, v11
	s_waitcnt vmcnt(11)
	v_mul_f32_e32 v160, v12, v128
	v_mul_f32_e32 v12, v16, v11
	v_mul_f32_e32 v161, v12, v129
	v_cvt_pk_bf16_f32 v160, v160, v161
	v_mul_f32_e32 v161, v62, v11
	v_mul_f32_e32 v161, v161, v130
	v_mul_f32_e32 v168, v19, v11
	v_mul_f32_e32 v168, v168, v131
	v_cvt_pk_bf16_f32 v161, v161, v168
	v_mul_f32_e32 v12, v18, v11
	s_waitcnt vmcnt(10)
	v_mul_f32_e32 v162, v12, v132
	v_mul_f32_e32 v12, v17, v11
	v_mul_f32_e32 v163, v12, v133
	v_cvt_pk_bf16_f32 v162, v162, v163
	v_mul_f32_e32 v163, v63, v11
	v_mul_f32_e32 v163, v163, v134
	v_mul_f32_e32 v168, v22, v11
	v_mul_f32_e32 v168, v168, v135
	v_cvt_pk_bf16_f32 v163, v163, v168
	s_nop 1
	v_permlane32_swap_b32_e32 v160, v162
	v_permlane32_swap_b32_e32 v161, v163
	global_store_dwordx4 v[8:9], v[160:163], off offset:128
	v_mul_f32_e32 v12, v21, v11
	s_waitcnt vmcnt(10)
	v_mul_f32_e32 v164, v12, v136
	v_mul_f32_e32 v12, v20, v11
	v_mul_f32_e32 v165, v12, v137
	v_cvt_pk_bf16_f32 v164, v164, v165
	v_mul_f32_e32 v165, v26, v11
	v_mul_f32_e32 v165, v165, v138
	v_mul_f32_e32 v168, v25, v11
	v_mul_f32_e32 v168, v168, v139
	v_cvt_pk_bf16_f32 v165, v165, v168
	v_mul_f32_e32 v12, v24, v11
	s_waitcnt vmcnt(9)
	v_mul_f32_e32 v166, v12, v140
	v_mul_f32_e32 v12, v23, v11
	v_mul_f32_e32 v167, v12, v141
	v_cvt_pk_bf16_f32 v166, v166, v167
	v_mul_f32_e32 v167, v71, v11
	v_mul_f32_e32 v167, v167, v142
	v_mul_f32_e32 v168, v30, v11
	v_mul_f32_e32 v168, v168, v143
	v_cvt_pk_bf16_f32 v167, v167, v168
	s_nop 1
	v_permlane32_swap_b32_e32 v164, v166
	v_permlane32_swap_b32_e32 v165, v167
	global_store_dwordx4 v[8:9], v[164:167], off offset:160
	v_mul_f32_e32 v12, v29, v11
	s_waitcnt vmcnt(9)
	v_mul_f32_e32 v160, v12, v144
	v_mul_f32_e32 v12, v27, v11
	v_mul_f32_e32 v161, v12, v145
	v_cvt_pk_bf16_f32 v160, v160, v161
	v_mul_f32_e32 v161, v77, v11
	v_mul_f32_e32 v161, v161, v146
	v_mul_f32_e32 v168, v76, v11
	v_mul_f32_e32 v168, v168, v147
	v_cvt_pk_bf16_f32 v161, v161, v168
	v_mul_f32_e32 v12, v74, v11
	s_waitcnt vmcnt(8)
	v_mul_f32_e32 v162, v12, v148
	v_mul_f32_e32 v12, v73, v11
	v_mul_f32_e32 v163, v12, v149
	v_cvt_pk_bf16_f32 v162, v162, v163
	v_mul_f32_e32 v163, v78, v11
	v_mul_f32_e32 v163, v163, v150
	v_mul_f32_e32 v168, v75, v11
	v_mul_f32_e32 v168, v168, v151
	v_cvt_pk_bf16_f32 v163, v163, v168
	s_nop 1
	v_permlane32_swap_b32_e32 v160, v162
	v_permlane32_swap_b32_e32 v161, v163
	global_store_dwordx4 v[8:9], v[160:163], off offset:192
	v_mul_f32_e32 v12, v72, v11
	s_waitcnt vmcnt(8)
	v_mul_f32_e32 v164, v12, v152
	v_mul_f32_e32 v12, v31, v11
	v_mul_f32_e32 v165, v12, v153
	v_cvt_pk_bf16_f32 v164, v164, v165
	v_mul_f32_e32 v165, v28, v11
	v_mul_f32_e32 v165, v165, v154
	v_mul_f32_e32 v168, v10, v11
	v_mul_f32_e32 v168, v168, v155
	v_cvt_pk_bf16_f32 v165, v165, v168
	s_waitcnt vmcnt(7)
	v_mul_f32_e32 v166, v6, v156
	v_mul_f32_e32 v6, v7, v11
	v_mul_f32_e32 v167, v6, v157
	v_cvt_pk_bf16_f32 v166, v166, v167
	v_mul_f32_e32 v167, v4, v11
	v_mul_f32_e32 v167, v167, v158
	v_mul_f32_e32 v168, v5, v11
	v_mul_f32_e32 v168, v168, v159
	v_cvt_pk_bf16_f32 v167, v167, v168
	s_nop 1
	v_permlane32_swap_b32_e32 v164, v166
	v_permlane32_swap_b32_e32 v165, v167
	global_store_dwordx4 v[8:9], v[164:167], off offset:224
	s_branch .LBB0_296
